# instruction placement (free form): e32 VALU widened to e64 where that puts the following 8-byte instruction on an 8-byte boundary, no padding
# speedup vs baseline: 1.0106x; 1.0106x over previous
.Lmy_ck_drE_a:
	s_waitcnt lgkmcnt(0)
	s_barrier
	s_cmpk_ge_u32 s62, 0x100
	s_cbranch_scc1 .Lmy_ck_mE_a
	s_bfe_u32 s96, s62, 0x20006
	s_mul_i32 s97, s96, 0x2700
	s_cmp_gt_u32 s96, 1
	s_cselect_b32 s101, 0x1300, 0
	s_add_i32 s97, s97, s101
	s_add_i32 s97, s97, 0x1c000
	s_mov_b32 s96, s97
	v_and_b32_e32 v72, 3, v233
	v_lshrrev_b32_e32 v73, 2, v233
	v_lshlrev_b32_e32 v72, 2, v72
	v_lshl_add_u32 v72, v73, 8, v72
	v_lshl_add_u32 v72, v234, 6, v72
	s_add_i32 s97, s96, 0x1000
	v_add_u32_e32 v78, s97, v72
	v_xor_b32_e32 v79, v224, v234
	v_lshl_add_u32 v79, v79, 4, s96
	ds_read_b128 v[96:99], v79
	ds_read_b128 v[100:103], v79 offset:1024
	ds_read_b128 v[104:107], v79 offset:2048
	ds_read_b128 v[108:111], v79 offset:3072
	ds_read_b32 v80, v78
	ds_read_b32 v81, v78 offset:16
	ds_read_b32 v82, v78 offset:32
	ds_read_b32 v83, v78 offset:48
	ds_read_b32 v84, v78 offset:1024
	ds_read_b32 v85, v78 offset:1040
	ds_read_b32 v86, v78 offset:1056
	ds_read_b32 v87, v78 offset:1072
	ds_read_b32 v88, v78 offset:2048
	ds_read_b32 v89, v78 offset:2064
	ds_read_b32 v90, v78 offset:2080
	ds_read_b32 v91, v78 offset:2096
	ds_read_b32 v92, v78 offset:3072
	ds_read_b32 v93, v78 offset:3088
	ds_read_b32 v94, v78 offset:3104
	ds_read_b32 v95, v78 offset:3120
	v_lshl_add_u32 v74, v224, 2, s96
	ds_write_b32 v74, v235 offset:9728
	v_add_u32_e32 v75, -1, v233
	v_mov_b32_e32 v76, -1
	v_cndmask_b32_e64 v75, v76, v75, s[98:99]
	v_cmp_lt_u32_e64 s[100:101], 7, v233
	v_add_u32_e32 v76, -8, v233
	v_and_b32_e32 v77, 1, v234
	v_cndmask_b32_e64 v75, v75, v76, s[100:101]
	v_lshlrev_b32_e32 v77, 2, v77
	v_sub_u32_e32 v76, v75, v77
	v_lshlrev_b32_e32 v77, 2, v234
	v_sub_u32_e32 v77, v233, v77
	v_add_u32_e32 v77, -1, v77
	s_waitcnt lgkmcnt(15)
	v_mfma_f32_16x16x4_f32 v[244:247], v80, v96, 0
	v_mfma_f32_16x16x4_f32 v[240:243], v81, v97, 0
	s_waitcnt lgkmcnt(14)
	v_mfma_f32_16x16x4_f32 v[244:247], v82, v98, v[244:247]
	s_waitcnt lgkmcnt(13)
	v_mfma_f32_16x16x4_f32 v[240:243], v83, v99, v[240:243]
	s_waitcnt lgkmcnt(12)
	v_mfma_f32_16x16x4_f32 v[244:247], v84, v100, v[244:247]
	s_waitcnt lgkmcnt(11)
	v_mfma_f32_16x16x4_f32 v[240:243], v85, v101, v[240:243]
	s_waitcnt lgkmcnt(10)
	v_mfma_f32_16x16x4_f32 v[244:247], v86, v102, v[244:247]
	s_waitcnt lgkmcnt(9)
	v_mfma_f32_16x16x4_f32 v[240:243], v87, v103, v[240:243]
	s_waitcnt lgkmcnt(8)
	v_mfma_f32_16x16x4_f32 v[244:247], v88, v104, v[244:247]
	s_waitcnt lgkmcnt(7)
	v_mfma_f32_16x16x4_f32 v[240:243], v89, v105, v[240:243]
	s_waitcnt lgkmcnt(6)
	v_mfma_f32_16x16x4_f32 v[244:247], v90, v106, v[244:247]
	s_waitcnt lgkmcnt(5)
	v_mfma_f32_16x16x4_f32 v[240:243], v91, v107, v[240:243]
	s_waitcnt lgkmcnt(4)
	v_mfma_f32_16x16x4_f32 v[244:247], v92, v108, v[244:247]
	s_waitcnt lgkmcnt(3)
	v_mfma_f32_16x16x4_f32 v[240:243], v93, v109, v[240:243]
	s_waitcnt lgkmcnt(2)
	v_mfma_f32_16x16x4_f32 v[244:247], v94, v110, v[244:247]
	s_waitcnt lgkmcnt(1)
	v_mfma_f32_16x16x4_f32 v[240:243], v95, v111, v[240:243]
	s_nop 9
	v_add_f32_e32 v244, v244, v240
	v_add_f32_e32 v245, v245, v241
	v_add_f32_e32 v246, v246, v242
	v_add_f32_e64 v247, v247, v243
	v_cmp_le_i32_e64 s[96:97], 0, v76
	v_cmp_le_i32_e64 s[100:101], 1, v76
	s_nop 0
	v_cndmask_b32_e64 v128, 0, v244, s[96:97]
	v_cndmask_b32_e64 v129, 0, v245, s[100:101]
	v_cmp_le_i32_e64 s[96:97], 2, v76
	v_cmp_le_i32_e64 s[100:101], 3, v76
	s_nop 0
	v_cndmask_b32_e64 v130, 0, v246, s[96:97]
	v_cndmask_b32_e64 v131, 0, v247, s[100:101]
	s_bfe_u32 s96, s62, 0x20006
	s_mul_i32 s97, s96, 0x2700
	s_cmp_gt_u32 s96, 1
	s_cselect_b32 s101, 0x1300, 0
	s_add_i32 s97, s97, s101
	s_add_i32 s97, s97, 0x1c000
	v_xor_b32_e64 v74, v224, v234
	v_lshl_add_u32 v74, v74, 4, s97
	ds_write_b128 v74, v[128:131] offset:8448
	v_lshlrev_b32_e64 v75, 7, v234
	v_lshl_add_u32 v75, v233, 2, v75
	v_add_u32_e64 v75, s97, v75
	v_cmp_le_i32_e64 s[96:97], 0, v77
	v_cmp_le_i32_e64 s[100:101], 1, v77
	s_nop 0
	v_cndmask_b32_e64 v132, 0, v244, s[96:97]
	v_cndmask_b32_e64 v133, 0, v245, s[100:101]
	v_cmp_le_i32_e64 s[96:97], 2, v77
	v_cmp_le_i32_e64 s[100:101], 3, v77
	s_nop 0
	v_cndmask_b32_e64 v134, 0, v246, s[96:97]
	v_cndmask_b32_e64 v135, 0, v247, s[100:101]
	s_mov_b64 exec, 0x00ff00ff
	ds_write_b32 v75, v132 offset:9472
	ds_write_b32 v75, v133 offset:9504
	ds_write_b32 v75, v134 offset:9536
	ds_write_b32 v75, v135 offset:9568
	s_mov_b64 exec, -1

.Lmy_ck_nz:
	s_mov_b32 s100, 0xe000
	s_cmp_eq_u32 s23, 0
	s_cselect_b32 s100, 0x1c000, s100
	s_mov_b32 s101, 0x12e00
	s_cselect_b32 s101, 0x22100, s101
	s_lshl_b32 s96, s23, 13
	s_add_i32 s97, s96, 0x18000
	s_add_i32 s96, s96, 0xa000
	v_add_u32_e32 v225, s100, v1
	v_add_u32_e32 v236, s100, v0
	v_add_u32_e32 v34, s100, v10
	v_add_u32_e32 v226, s100, v2
	v_add_u32_e32 v227, s100, v3
	v_add_u32_e32 v228, s100, v4
	v_add_u32_e32 v229, s100, v5
	v_add_u32_e32 v237, s100, v6
	v_add_u32_e32 v238, s100, v7
	v_add_u32_e32 v230, s96, v8
	v_add_u32_e32 v239, s96, v9
	v_add_u32_e32 v231, s97, v8
	v_add_u32_e32 v26, s101, v1
	v_add_u32_e32 v27, s101, v0
	v_add_u32_e32 v35, s101, v10
	v_add_u32_e32 v28, s101, v2
	v_add_u32_e32 v29, s101, v3
	v_add_u32_e32 v30, s101, v4
	v_add_u32_e32 v31, s101, v5
	v_add_u32_e32 v32, s101, v6
	v_add_u32_e32 v33, s101, v7
	ds_read_b64 v[80:81], v237
	ds_read_b64 v[82:83], v238
	ds_read_b32 v36, v239
	ds_read_b32 v37, v239 offset:256
	ds_read_b128 v[88:91], v225
	ds_read_b128 v[92:95], v225 offset:1024
	ds_read_b128 v[96:99], v225 offset:2048
	ds_read_b128 v[100:103], v225 offset:3072
	ds_read_b32 v104, v227 offset:4
	ds_read_b32 v105, v227 offset:76
	ds_read_b64 v[106:107], v227 offset:8
	ds_read_b64 v[108:109], v227 offset:40
	ds_read_b32 v126, v229 offset:4
	ds_read_b32 v127, v229 offset:76
	ds_read_b64 v[128:129], v229 offset:8
	ds_read_b64 v[130:131], v229 offset:40
	ds_read_b64 v[110:111], v228
	ds_read_b64 v[112:113], v228 offset:32
	ds_read_b64 v[114:115], v228 offset:64
	ds_read_b64 v[116:117], v228 offset:96
	ds_read_b64 v[118:119], v228 offset:8
	ds_read_b64 v[120:121], v228 offset:40
	ds_read_b64 v[122:123], v228 offset:72
	ds_read_b64 v[124:125], v228 offset:104
	s_waitcnt lgkmcnt(15)
	v_mfma_f32_16x16x4_f32 v[240:243], v80, v36, 0
	v_mfma_f32_16x16x4_f32 v[240:243], v81, v37, v[240:243]
	v_mfma_f32_16x16x4_f32 v[240:243], v88, v208, v[240:243]
	ds_read_b64 v[186:187], v34
	ds_read_b64 v[190:191], v34 offset:1024
	v_mfma_f32_16x16x4_f32 v[244:247], v89, v209, 0
	ds_read_b64 v[194:195], v34 offset:2048
	ds_read_b64 v[198:199], v34 offset:3072
	v_mfma_f32_16x16x4_f32 v[240:243], v90, v210, v[240:243]
	ds_read_b64 v[184:185], v236
	ds_read_b64 v[188:189], v236 offset:1024
	ds_read_b64 v[132:133], v237 offset:9984
	v_mfma_f32_16x16x4_f32 v[244:247], v91, v211, v[244:247]
	ds_read_b64 v[134:135], v238 offset:9984
	ds_read_b64 v[192:193], v236 offset:2048
	ds_read_b64 v[196:197], v236 offset:3072
	v_mfma_f32_16x16x4_f32 v[240:243], v92, v212, v[240:243]
	ds_read_b32 v38, v239 offset:2048
	ds_read_b32 v39, v239 offset:2304
	ds_read_b128 v[140:143], v225 offset:9984
	v_mfma_f32_16x16x4_f32 v[244:247], v93, v213, v[244:247]
	ds_read_b128 v[144:147], v225 offset:11008
	ds_read_b128 v[148:151], v225 offset:12032
	ds_read_b128 v[152:155], v225 offset:13056
	v_mfma_f32_16x16x4_f32 v[240:243], v94, v214, v[240:243]
	ds_read_b32 v156, v227 offset:9988
	ds_read_b32 v157, v227 offset:10060
	v_mfma_f32_16x16x4_f32 v[244:247], v95, v215, v[244:247]
	ds_read_b64 v[158:159], v227 offset:9992
	ds_read_b64 v[160:161], v227 offset:10024
	v_mfma_f32_16x16x4_f32 v[240:243], v96, v216, v[240:243]
	ds_read_b32 v178, v229 offset:9988
	ds_read_b32 v179, v229 offset:10060
	v_mfma_f32_16x16x4_f32 v[244:247], v97, v217, v[244:247]
	ds_read_b64 v[180:181], v229 offset:9992
	ds_read_b64 v[182:183], v229 offset:10024
	v_mfma_f32_16x16x4_f32 v[240:243], v98, v218, v[240:243]
	ds_read_b64 v[162:163], v228 offset:9984
	ds_read_b64 v[164:165], v228 offset:10016
	v_mfma_f32_16x16x4_f32 v[244:247], v99, v219, v[244:247]
	ds_read_b64 v[166:167], v228 offset:10048
	ds_read_b64 v[168:169], v228 offset:10080
	v_mfma_f32_16x16x4_f32 v[240:243], v100, v220, v[240:243]
	ds_read_b64 v[170:171], v228 offset:9992
	ds_read_b64 v[172:173], v228 offset:10024
	v_mfma_f32_16x16x4_f32 v[244:247], v101, v221, v[244:247]
	ds_read_b64 v[174:175], v228 offset:10056
	ds_read_b64 v[176:177], v228 offset:10088
	v_mfma_f32_16x16x4_f32 v[240:243], v102, v222, v[240:243]
	v_mfma_f32_16x16x4_f32 v[244:247], v103, v223, v[244:247]
	s_waitcnt lgkmcnt(15)
	v_mfma_f32_16x16x4_f32 v[208:211], v186, v36, v[208:211]
	s_nop 2
	v_pk_add_f32 v[240:241], v[240:241], v[244:245]
	v_pk_add_f32 v[242:243], v[242:243], v[246:247]
	v_fmac_f32_e32 v241, v104, v240
	v_mfma_f32_16x16x4_f32 v[212:215], v190, v36, v[212:215]
	v_pk_fma_f32 v[242:243], v[106:107], v[240:241], v[242:243] op_sel:[0,0,0] op_sel_hi:[1,0,1]
	v_pk_fma_f32 v[242:243], v[108:109], v[240:241], v[242:243] op_sel:[0,1,0] op_sel_hi:[1,1,1]
	v_fmac_f32_e64 v243, v105, v242
	v_mfma_f32_16x16x4_f32 v[216:219], v194, v36, v[216:219]
	ds_bpermute_b32 v204, v232, v240
	ds_bpermute_b32 v205, v232, v241
	ds_bpermute_b32 v206, v232, v242
	v_mfma_f32_16x16x4_f32 v[72:75], v132, v38, 0
	ds_bpermute_b32 v207, v232, v243
	s_waitcnt lgkmcnt(2)
	v_pk_fma_f32 v[240:241], v[110:111], v[204:205], v[240:241] op_sel:[0,0,0] op_sel_hi:[1,0,1]
	v_pk_fma_f32 v[240:241], v[112:113], v[204:205], v[240:241] op_sel:[0,1,0] op_sel_hi:[1,1,1]
	v_mfma_f32_16x16x4_f32 v[72:75], v133, v39, v[72:75]
	s_waitcnt lgkmcnt(0)
	v_pk_fma_f32 v[240:241], v[114:115], v[206:207], v[240:241] op_sel:[0,0,0] op_sel_hi:[1,0,1]
	v_pk_fma_f32 v[240:241], v[116:117], v[206:207], v[240:241] op_sel:[0,1,0] op_sel_hi:[1,1,1]
	v_pk_fma_f32 v[242:243], v[118:119], v[204:205], v[242:243] op_sel:[0,0,0] op_sel_hi:[1,0,1]
	v_mfma_f32_16x16x4_f32 v[220:223], v198, v36, v[220:223]
	v_pk_fma_f32 v[242:243], v[120:121], v[204:205], v[242:243] op_sel:[0,1,0] op_sel_hi:[1,1,1]
	v_pk_fma_f32 v[242:243], v[122:123], v[206:207], v[242:243] op_sel:[0,0,0] op_sel_hi:[1,0,1]
	v_pk_fma_f32 v[242:243], v[124:125], v[206:207], v[242:243] op_sel:[0,1,0] op_sel_hi:[1,1,1]
	v_mfma_f32_16x16x4_f32 v[208:211], v187, v37, v[208:211]
	v_fmac_f32_e64 v241, v126, v240
	v_pk_fma_f32 v[242:243], v[128:129], v[240:241], v[242:243] op_sel:[0,0,0] op_sel_hi:[1,0,1]
	v_pk_fma_f32 v[242:243], v[130:131], v[240:241], v[242:243] op_sel:[0,1,0] op_sel_hi:[1,1,1]
	v_mfma_f32_16x16x4_f32 v[212:215], v191, v37, v[212:215]
	v_fmac_f32_e32 v243, v127, v242
	v_mov_b32_e32 v252, v240
	v_mov_b32_e64 v253, v241
	v_mfma_f32_16x16x4_f32 v[216:219], v195, v37, v[216:219]
	v_mov_b32_e32 v254, v242
	v_mov_b32_e32 v255, v243
	s_nop 0
	v_permlane32_swap_b32_e32 v252, v254
	v_mfma_f32_16x16x4_f32 v[220:223], v199, v37, v[220:223]
	v_permlane32_swap_b32_e32 v253, v255
	v_mfma_f32_16x16x4_f32 v[208:211], v184, v252, v[208:211]
	ds_read_b128 v[88:91], v226
	v_mfma_f32_16x16x4_f32 v[212:215], v188, v252, v[212:215]
	ds_read_b128 v[92:95], v226 offset:64
	v_mfma_f32_16x16x4_f32 v[216:219], v192, v252, v[216:219]
	ds_read_b128 v[96:99], v226 offset:128
	v_mfma_f32_16x16x4_f32 v[220:223], v196, v252, v[220:223]
	ds_read_b128 v[100:103], v226 offset:192
	v_mfma_f32_16x16x4_f32 v[208:211], v185, v253, v[208:211]
	v_mfma_f32_16x16x4_f32 v[212:215], v189, v253, v[212:215]
	v_mfma_f32_16x16x4_f32 v[216:219], v193, v253, v[216:219]
	v_mfma_f32_16x16x4_f32 v[220:223], v197, v253, v[220:223]
	v_mfma_f32_16x16x4_f32 v[248:251], v82, v252, v[240:243]
	v_mfma_f32_16x16x4_f32 v[248:251], v83, v253, v[248:251]
	s_waitcnt lgkmcnt(3)
	v_pk_mul_f32 v[208:209], v[208:209], v[88:89]
	v_pk_mul_f32 v[210:211], v[210:211], v[90:91]
	s_nop 0
	v_mfma_f32_16x16x4_f32 v[72:75], v140, v208, v[72:75]
	s_waitcnt lgkmcnt(2)
	v_pk_mul_f32 v[212:213], v[212:213], v[92:93]
	v_mfma_f32_16x16x4_f32 v[244:247], v141, v209, 0
	v_pk_mul_f32 v[214:215], v[214:215], v[94:95]
	v_mfma_f32_16x16x4_f32 v[72:75], v142, v210, v[72:75]
	s_waitcnt lgkmcnt(1)
	v_pk_mul_f32 v[216:217], v[216:217], v[96:97]
	v_mfma_f32_16x16x4_f32 v[244:247], v143, v211, v[244:247]
	v_pk_mul_f32 v[218:219], v[218:219], v[98:99]
	v_mfma_f32_16x16x4_f32 v[72:75], v144, v212, v[72:75]
	s_waitcnt lgkmcnt(0)
	v_pk_mul_f32 v[220:221], v[220:221], v[100:101]
	v_mfma_f32_16x16x4_f32 v[244:247], v145, v213, v[244:247]
	v_pk_mul_f32 v[222:223], v[222:223], v[102:103]
	v_mfma_f32_16x16x4_f32 v[72:75], v146, v214, v[72:75]
	s_mov_b64 exec, s[98:99]
	ds_write_b32 v231, v248
	ds_write_b32 v231, v249 offset:256
	ds_write_b32 v231, v250 offset:512
	ds_write_b32 v231, v251 offset:768
	s_mov_b64 exec, -1
	ds_read_b64 v[186:187], v34 offset:9984
	ds_read_b64 v[190:191], v34 offset:11008
	v_mfma_f32_16x16x4_f32 v[244:247], v147, v215, v[244:247]
	ds_read_b64 v[194:195], v34 offset:12032
	ds_read_b64 v[198:199], v34 offset:13056
	v_mfma_f32_16x16x4_f32 v[72:75], v148, v216, v[72:75]
	ds_read_b64 v[184:185], v236 offset:9984
	ds_read_b64 v[188:189], v236 offset:11008
	ds_read_b64 v[80:81], v32
	v_mfma_f32_16x16x4_f32 v[244:247], v149, v217, v[244:247]
	ds_read_b64 v[82:83], v33
	ds_read_b32 v36, v239 offset:4096
	ds_read_b64 v[192:193], v236 offset:12032
	v_mfma_f32_16x16x4_f32 v[72:75], v150, v218, v[72:75]
	ds_read_b64 v[196:197], v236 offset:13056
	ds_read_b32 v37, v239 offset:4352
	ds_read_b128 v[88:91], v26
	v_mfma_f32_16x16x4_f32 v[244:247], v151, v219, v[244:247]
	ds_read_b128 v[92:95], v26 offset:1024
	ds_read_b128 v[96:99], v26 offset:2048
	ds_read_b128 v[100:103], v26 offset:3072
	v_mfma_f32_16x16x4_f32 v[72:75], v152, v220, v[72:75]
	ds_read_b32 v104, v29 offset:4
	ds_read_b32 v105, v29 offset:76
	ds_read_b64 v[106:107], v29 offset:8
	v_mfma_f32_16x16x4_f32 v[244:247], v153, v221, v[244:247]
	ds_read_b64 v[108:109], v29 offset:40
	ds_read_b32 v126, v31 offset:4
	ds_read_b32 v127, v31 offset:76
	v_mfma_f32_16x16x4_f32 v[72:75], v154, v222, v[72:75]
	ds_read_b64 v[128:129], v31 offset:8
	ds_read_b64 v[130:131], v31 offset:40
	ds_read_b64 v[110:111], v30
	v_mfma_f32_16x16x4_f32 v[244:247], v155, v223, v[244:247]
	ds_read_b64 v[112:113], v30 offset:32
	ds_read_b64 v[114:115], v30 offset:64
	ds_read_b64 v[116:117], v30 offset:96
	ds_read_b64 v[118:119], v30 offset:8
	ds_read_b64 v[120:121], v30 offset:40
	ds_read_b64 v[122:123], v30 offset:72
	ds_read_b64 v[124:125], v30 offset:104
	s_waitcnt lgkmcnt(15)
	v_mfma_f32_16x16x4_f32 v[208:211], v186, v38, v[208:211]
	s_nop 1
	v_pk_add_f32 v[72:73], v[72:73], v[244:245]
	v_pk_add_f32 v[74:75], v[74:75], v[246:247]
	v_fmac_f32_e64 v73, v156, v72
	v_mfma_f32_16x16x4_f32 v[212:215], v190, v38, v[212:215]
	v_pk_fma_f32 v[74:75], v[158:159], v[72:73], v[74:75] op_sel:[0,0,0] op_sel_hi:[1,0,1]
	v_pk_fma_f32 v[74:75], v[160:161], v[72:73], v[74:75] op_sel:[0,1,0] op_sel_hi:[1,1,1]
	v_fmac_f32_e64 v75, v157, v74
	v_mfma_f32_16x16x4_f32 v[216:219], v194, v38, v[216:219]
	ds_bpermute_b32 v204, v232, v72
	ds_bpermute_b32 v205, v232, v73
	ds_bpermute_b32 v206, v232, v74
	v_mfma_f32_16x16x4_f32 v[240:243], v80, v36, 0
	ds_bpermute_b32 v207, v232, v75
	s_waitcnt lgkmcnt(2)
	v_pk_fma_f32 v[72:73], v[162:163], v[204:205], v[72:73] op_sel:[0,0,0] op_sel_hi:[1,0,1]
	v_pk_fma_f32 v[72:73], v[164:165], v[204:205], v[72:73] op_sel:[0,1,0] op_sel_hi:[1,1,1]
	v_mfma_f32_16x16x4_f32 v[240:243], v81, v37, v[240:243]
	s_waitcnt lgkmcnt(0)
	v_pk_fma_f32 v[72:73], v[166:167], v[206:207], v[72:73] op_sel:[0,0,0] op_sel_hi:[1,0,1]
	v_pk_fma_f32 v[72:73], v[168:169], v[206:207], v[72:73] op_sel:[0,1,0] op_sel_hi:[1,1,1]
	v_pk_fma_f32 v[74:75], v[170:171], v[204:205], v[74:75] op_sel:[0,0,0] op_sel_hi:[1,0,1]
	v_mfma_f32_16x16x4_f32 v[220:223], v198, v38, v[220:223]
	v_pk_fma_f32 v[74:75], v[172:173], v[204:205], v[74:75] op_sel:[0,1,0] op_sel_hi:[1,1,1]
	v_pk_fma_f32 v[74:75], v[174:175], v[206:207], v[74:75] op_sel:[0,0,0] op_sel_hi:[1,0,1]
	v_pk_fma_f32 v[74:75], v[176:177], v[206:207], v[74:75] op_sel:[0,1,0] op_sel_hi:[1,1,1]
	v_mfma_f32_16x16x4_f32 v[208:211], v187, v39, v[208:211]
	v_fmac_f32_e64 v73, v178, v72
	v_pk_fma_f32 v[74:75], v[180:181], v[72:73], v[74:75] op_sel:[0,0,0] op_sel_hi:[1,0,1]
	v_pk_fma_f32 v[74:75], v[182:183], v[72:73], v[74:75] op_sel:[0,1,0] op_sel_hi:[1,1,1]
	v_mfma_f32_16x16x4_f32 v[212:215], v191, v39, v[212:215]
	v_fmac_f32_e32 v75, v179, v74
	v_mov_b32_e32 v252, v72
	v_mov_b32_e64 v253, v73
	v_mfma_f32_16x16x4_f32 v[216:219], v195, v39, v[216:219]
	v_mov_b32_e32 v254, v74
	v_mov_b32_e32 v255, v75
	s_nop 0
	v_permlane32_swap_b32_e32 v252, v254
	v_mfma_f32_16x16x4_f32 v[220:223], v199, v39, v[220:223]
	v_permlane32_swap_b32_e32 v253, v255
	v_mfma_f32_16x16x4_f32 v[208:211], v184, v252, v[208:211]
	ds_read_b128 v[140:143], v226 offset:9984
	v_mfma_f32_16x16x4_f32 v[212:215], v188, v252, v[212:215]
	ds_read_b128 v[144:147], v226 offset:10048
	v_mfma_f32_16x16x4_f32 v[216:219], v192, v252, v[216:219]
	ds_read_b128 v[148:151], v226 offset:10112
	v_mfma_f32_16x16x4_f32 v[220:223], v196, v252, v[220:223]
	ds_read_b128 v[152:155], v226 offset:10176
	v_mfma_f32_16x16x4_f32 v[208:211], v185, v253, v[208:211]
	v_mfma_f32_16x16x4_f32 v[212:215], v189, v253, v[212:215]
	v_mfma_f32_16x16x4_f32 v[216:219], v193, v253, v[216:219]
	v_mfma_f32_16x16x4_f32 v[220:223], v197, v253, v[220:223]
	v_mfma_f32_16x16x4_f32 v[248:251], v134, v252, v[72:75]
	v_mfma_f32_16x16x4_f32 v[248:251], v135, v253, v[248:251]
	s_waitcnt lgkmcnt(3)
	v_pk_mul_f32 v[208:209], v[208:209], v[140:141]
	v_pk_mul_f32 v[210:211], v[210:211], v[142:143]
	s_nop 0
	v_mfma_f32_16x16x4_f32 v[240:243], v88, v208, v[240:243]
	s_waitcnt lgkmcnt(2)
	v_pk_mul_f32 v[212:213], v[212:213], v[144:145]
	v_mfma_f32_16x16x4_f32 v[244:247], v89, v209, 0
	v_pk_mul_f32 v[214:215], v[214:215], v[146:147]
	v_mfma_f32_16x16x4_f32 v[240:243], v90, v210, v[240:243]
	s_waitcnt lgkmcnt(1)
	v_pk_mul_f32 v[216:217], v[216:217], v[148:149]
	v_mfma_f32_16x16x4_f32 v[244:247], v91, v211, v[244:247]
	v_pk_mul_f32 v[218:219], v[218:219], v[150:151]
	v_mfma_f32_16x16x4_f32 v[240:243], v92, v212, v[240:243]
	s_waitcnt lgkmcnt(0)
	v_pk_mul_f32 v[220:221], v[220:221], v[152:153]
	v_mfma_f32_16x16x4_f32 v[244:247], v93, v213, v[244:247]
	v_pk_mul_f32 v[222:223], v[222:223], v[154:155]
	v_mfma_f32_16x16x4_f32 v[240:243], v94, v214, v[240:243]
	s_mov_b64 exec, s[98:99]
	ds_write_b32 v231, v248 offset:2048
	ds_write_b32 v231, v249 offset:2304
	ds_write_b32 v231, v250 offset:2560
	ds_write_b32 v231, v251 offset:2816
	s_mov_b64 exec, -1
	ds_read_b64 v[186:187], v35
	ds_read_b64 v[190:191], v35 offset:1024
	v_mfma_f32_16x16x4_f32 v[244:247], v95, v215, v[244:247]
	ds_read_b64 v[194:195], v35 offset:2048
	ds_read_b64 v[198:199], v35 offset:3072
	v_mfma_f32_16x16x4_f32 v[240:243], v96, v216, v[240:243]
	ds_read_b64 v[184:185], v27
	ds_read_b64 v[188:189], v27 offset:1024
	ds_read_b64 v[132:133], v32 offset:9984
	v_mfma_f32_16x16x4_f32 v[244:247], v97, v217, v[244:247]
	ds_read_b64 v[134:135], v33 offset:9984
	ds_read_b32 v38, v239 offset:6144
	ds_read_b64 v[192:193], v27 offset:2048
	v_mfma_f32_16x16x4_f32 v[240:243], v98, v218, v[240:243]
	ds_read_b64 v[196:197], v27 offset:3072
	ds_read_b32 v39, v239 offset:6400
	ds_read_b128 v[140:143], v26 offset:9984
	v_mfma_f32_16x16x4_f32 v[244:247], v99, v219, v[244:247]
	ds_read_b128 v[144:147], v26 offset:11008
	ds_read_b128 v[148:151], v26 offset:12032
	ds_read_b128 v[152:155], v26 offset:13056
	v_mfma_f32_16x16x4_f32 v[240:243], v100, v220, v[240:243]
	ds_read_b32 v156, v29 offset:9988
	ds_read_b32 v157, v29 offset:10060
	ds_read_b64 v[158:159], v29 offset:9992
	v_mfma_f32_16x16x4_f32 v[244:247], v101, v221, v[244:247]
	ds_read_b64 v[160:161], v29 offset:10024
	ds_read_b32 v178, v31 offset:9988
	ds_read_b32 v179, v31 offset:10060
	v_mfma_f32_16x16x4_f32 v[240:243], v102, v222, v[240:243]
	ds_read_b64 v[180:181], v31 offset:9992
	ds_read_b64 v[182:183], v31 offset:10024
	ds_read_b64 v[162:163], v30 offset:9984
	v_mfma_f32_16x16x4_f32 v[244:247], v103, v223, v[244:247]
	ds_read_b64 v[164:165], v30 offset:10016
	ds_read_b64 v[166:167], v30 offset:10048
	ds_read_b64 v[168:169], v30 offset:10080
	ds_read_b64 v[170:171], v30 offset:9992
	ds_read_b64 v[172:173], v30 offset:10024
	ds_read_b64 v[174:175], v30 offset:10056
	ds_read_b64 v[176:177], v30 offset:10088
	s_waitcnt lgkmcnt(15)
	v_mfma_f32_16x16x4_f32 v[208:211], v186, v36, v[208:211]
	s_nop 1
	v_pk_add_f32 v[240:241], v[240:241], v[244:245]
	v_pk_add_f32 v[242:243], v[242:243], v[246:247]
	v_fmac_f32_e64 v241, v104, v240
	v_mfma_f32_16x16x4_f32 v[212:215], v190, v36, v[212:215]
	v_pk_fma_f32 v[242:243], v[106:107], v[240:241], v[242:243] op_sel:[0,0,0] op_sel_hi:[1,0,1]
	v_pk_fma_f32 v[242:243], v[108:109], v[240:241], v[242:243] op_sel:[0,1,0] op_sel_hi:[1,1,1]
	v_fmac_f32_e64 v243, v105, v242
	v_mfma_f32_16x16x4_f32 v[216:219], v194, v36, v[216:219]
	ds_bpermute_b32 v204, v232, v240
	ds_bpermute_b32 v205, v232, v241
	ds_bpermute_b32 v206, v232, v242
	v_mfma_f32_16x16x4_f32 v[72:75], v132, v38, 0
	ds_bpermute_b32 v207, v232, v243
	s_waitcnt lgkmcnt(2)
	v_pk_fma_f32 v[240:241], v[110:111], v[204:205], v[240:241] op_sel:[0,0,0] op_sel_hi:[1,0,1]
	v_pk_fma_f32 v[240:241], v[112:113], v[204:205], v[240:241] op_sel:[0,1,0] op_sel_hi:[1,1,1]
	v_mfma_f32_16x16x4_f32 v[72:75], v133, v39, v[72:75]
	s_waitcnt lgkmcnt(0)
	v_pk_fma_f32 v[240:241], v[114:115], v[206:207], v[240:241] op_sel:[0,0,0] op_sel_hi:[1,0,1]
	v_pk_fma_f32 v[240:241], v[116:117], v[206:207], v[240:241] op_sel:[0,1,0] op_sel_hi:[1,1,1]
	v_pk_fma_f32 v[242:243], v[118:119], v[204:205], v[242:243] op_sel:[0,0,0] op_sel_hi:[1,0,1]
	v_mfma_f32_16x16x4_f32 v[220:223], v198, v36, v[220:223]
	v_pk_fma_f32 v[242:243], v[120:121], v[204:205], v[242:243] op_sel:[0,1,0] op_sel_hi:[1,1,1]
	v_pk_fma_f32 v[242:243], v[122:123], v[206:207], v[242:243] op_sel:[0,0,0] op_sel_hi:[1,0,1]
	v_pk_fma_f32 v[242:243], v[124:125], v[206:207], v[242:243] op_sel:[0,1,0] op_sel_hi:[1,1,1]
	v_mfma_f32_16x16x4_f32 v[208:211], v187, v37, v[208:211]
	v_fmac_f32_e64 v241, v126, v240
	v_pk_fma_f32 v[242:243], v[128:129], v[240:241], v[242:243] op_sel:[0,0,0] op_sel_hi:[1,0,1]
	v_pk_fma_f32 v[242:243], v[130:131], v[240:241], v[242:243] op_sel:[0,1,0] op_sel_hi:[1,1,1]
	v_mfma_f32_16x16x4_f32 v[212:215], v191, v37, v[212:215]
	v_fmac_f32_e32 v243, v127, v242
	v_mov_b32_e32 v252, v240
	v_mov_b32_e64 v253, v241
	v_mfma_f32_16x16x4_f32 v[216:219], v195, v37, v[216:219]
	v_mov_b32_e32 v254, v242
	v_mov_b32_e32 v255, v243
	s_nop 0
	v_permlane32_swap_b32_e32 v252, v254
	v_mfma_f32_16x16x4_f32 v[220:223], v199, v37, v[220:223]
	v_permlane32_swap_b32_e32 v253, v255
	v_mfma_f32_16x16x4_f32 v[208:211], v184, v252, v[208:211]
	ds_read_b128 v[88:91], v28
	v_mfma_f32_16x16x4_f32 v[212:215], v188, v252, v[212:215]
	ds_read_b128 v[92:95], v28 offset:64
	v_mfma_f32_16x16x4_f32 v[216:219], v192, v252, v[216:219]
	ds_read_b128 v[96:99], v28 offset:128
	v_mfma_f32_16x16x4_f32 v[220:223], v196, v252, v[220:223]
	ds_read_b128 v[100:103], v28 offset:192
	v_mfma_f32_16x16x4_f32 v[208:211], v185, v253, v[208:211]
	v_mfma_f32_16x16x4_f32 v[212:215], v189, v253, v[212:215]
	v_mfma_f32_16x16x4_f32 v[216:219], v193, v253, v[216:219]
	v_mfma_f32_16x16x4_f32 v[220:223], v197, v253, v[220:223]
	v_mfma_f32_16x16x4_f32 v[248:251], v82, v252, v[240:243]
	v_mfma_f32_16x16x4_f32 v[248:251], v83, v253, v[248:251]
	s_waitcnt lgkmcnt(3)
	v_pk_mul_f32 v[208:209], v[208:209], v[88:89]
	v_pk_mul_f32 v[210:211], v[210:211], v[90:91]
	s_nop 0
	v_mfma_f32_16x16x4_f32 v[72:75], v140, v208, v[72:75]
	s_waitcnt lgkmcnt(2)
	v_pk_mul_f32 v[212:213], v[212:213], v[92:93]
	v_mfma_f32_16x16x4_f32 v[244:247], v141, v209, 0
	v_pk_mul_f32 v[214:215], v[214:215], v[94:95]
	v_mfma_f32_16x16x4_f32 v[72:75], v142, v210, v[72:75]
	s_waitcnt lgkmcnt(1)
	v_pk_mul_f32 v[216:217], v[216:217], v[96:97]
	v_mfma_f32_16x16x4_f32 v[244:247], v143, v211, v[244:247]
	v_pk_mul_f32 v[218:219], v[218:219], v[98:99]
	v_mfma_f32_16x16x4_f32 v[72:75], v144, v212, v[72:75]
	s_waitcnt lgkmcnt(0)
	v_pk_mul_f32 v[220:221], v[220:221], v[100:101]
	v_mfma_f32_16x16x4_f32 v[244:247], v145, v213, v[244:247]
	v_pk_mul_f32 v[222:223], v[222:223], v[102:103]
	v_mfma_f32_16x16x4_f32 v[72:75], v146, v214, v[72:75]
	s_mov_b64 exec, s[98:99]
	ds_write_b32 v231, v248 offset:4096
	ds_write_b32 v231, v249 offset:4352
	ds_write_b32 v231, v250 offset:4608
	ds_write_b32 v231, v251 offset:4864
	s_mov_b64 exec, -1
	ds_read_b64 v[186:187], v35 offset:9984
	ds_read_b64 v[190:191], v35 offset:11008
	v_mfma_f32_16x16x4_f32 v[244:247], v147, v215, v[244:247]
	ds_read_b64 v[194:195], v35 offset:12032
	ds_read_b64 v[198:199], v35 offset:13056
	v_mfma_f32_16x16x4_f32 v[72:75], v148, v216, v[72:75]
	ds_read_b64 v[184:185], v27 offset:9984
	ds_read_b64 v[188:189], v27 offset:11008
	v_mfma_f32_16x16x4_f32 v[244:247], v149, v217, v[244:247]
	ds_read_b64 v[192:193], v27 offset:12032
	ds_read_b64 v[196:197], v27 offset:13056
	v_mfma_f32_16x16x4_f32 v[72:75], v150, v218, v[72:75]
	v_mfma_f32_16x16x4_f32 v[244:247], v151, v219, v[244:247]
	v_mfma_f32_16x16x4_f32 v[72:75], v152, v220, v[72:75]
	v_mfma_f32_16x16x4_f32 v[244:247], v153, v221, v[244:247]
	v_mfma_f32_16x16x4_f32 v[72:75], v154, v222, v[72:75]
	v_mfma_f32_16x16x4_f32 v[244:247], v155, v223, v[244:247]
	s_waitcnt lgkmcnt(7)
	v_mfma_f32_16x16x4_f32 v[208:211], v186, v38, v[208:211]
	s_nop 2
	v_pk_add_f32 v[72:73], v[72:73], v[244:245]
	v_pk_add_f32 v[74:75], v[74:75], v[246:247]
	v_fmac_f32_e32 v73, v156, v72
	s_waitcnt lgkmcnt(6)
	v_mfma_f32_16x16x4_f32 v[212:215], v190, v38, v[212:215]
	v_pk_fma_f32 v[74:75], v[158:159], v[72:73], v[74:75] op_sel:[0,0,0] op_sel_hi:[1,0,1]
	v_pk_fma_f32 v[74:75], v[160:161], v[72:73], v[74:75] op_sel:[0,1,0] op_sel_hi:[1,1,1]
	v_fmac_f32_e32 v75, v157, v74
	s_waitcnt lgkmcnt(5)
	v_mfma_f32_16x16x4_f32 v[216:219], v194, v38, v[216:219]
	ds_bpermute_b32 v204, v232, v72
	ds_bpermute_b32 v205, v232, v73
	ds_bpermute_b32 v206, v232, v74
	s_waitcnt lgkmcnt(7)
	v_mfma_f32_16x16x4_f32 v[220:223], v198, v38, v[220:223]
	ds_bpermute_b32 v207, v232, v75
	s_waitcnt lgkmcnt(2)
	v_pk_fma_f32 v[72:73], v[162:163], v[204:205], v[72:73] op_sel:[0,0,0] op_sel_hi:[1,0,1]
	v_pk_fma_f32 v[72:73], v[164:165], v[204:205], v[72:73] op_sel:[0,1,0] op_sel_hi:[1,1,1]
	v_mfma_f32_16x16x4_f32 v[208:211], v187, v39, v[208:211]
	s_waitcnt lgkmcnt(0)
	v_pk_fma_f32 v[72:73], v[166:167], v[206:207], v[72:73] op_sel:[0,0,0] op_sel_hi:[1,0,1]
	v_pk_fma_f32 v[72:73], v[168:169], v[206:207], v[72:73] op_sel:[0,1,0] op_sel_hi:[1,1,1]
	v_pk_fma_f32 v[74:75], v[170:171], v[204:205], v[74:75] op_sel:[0,0,0] op_sel_hi:[1,0,1]
	v_mfma_f32_16x16x4_f32 v[212:215], v191, v39, v[212:215]
	v_pk_fma_f32 v[74:75], v[172:173], v[204:205], v[74:75] op_sel:[0,1,0] op_sel_hi:[1,1,1]
	v_pk_fma_f32 v[74:75], v[174:175], v[206:207], v[74:75] op_sel:[0,0,0] op_sel_hi:[1,0,1]
	v_pk_fma_f32 v[74:75], v[176:177], v[206:207], v[74:75] op_sel:[0,1,0] op_sel_hi:[1,1,1]
	v_mfma_f32_16x16x4_f32 v[216:219], v195, v39, v[216:219]
	v_fmac_f32_e32 v73, v178, v72
	v_pk_fma_f32 v[74:75], v[180:181], v[72:73], v[74:75] op_sel:[0,0,0] op_sel_hi:[1,0,1]
	v_pk_fma_f32 v[74:75], v[182:183], v[72:73], v[74:75] op_sel:[0,1,0] op_sel_hi:[1,1,1]
	v_mfma_f32_16x16x4_f32 v[220:223], v199, v39, v[220:223]
	v_fmac_f32_e32 v75, v179, v74
	v_mov_b32_e32 v252, v72
	v_mov_b32_e32 v253, v73
	v_mov_b32_e32 v254, v74
	v_mov_b32_e32 v255, v75
	s_nop 0
	v_permlane32_swap_b32_e32 v252, v254
	v_permlane32_swap_b32_e32 v253, v255
	s_nop 0
	v_mfma_f32_16x16x4_f32 v[208:211], v184, v252, v[208:211]
	ds_read_b128 v[140:143], v28 offset:9984
	v_mfma_f32_16x16x4_f32 v[212:215], v188, v252, v[212:215]
	ds_read_b128 v[144:147], v28 offset:10048
	v_mfma_f32_16x16x4_f32 v[216:219], v192, v252, v[216:219]
	ds_read_b128 v[148:151], v28 offset:10112
	v_mfma_f32_16x16x4_f32 v[220:223], v196, v252, v[220:223]
	ds_read_b128 v[152:155], v28 offset:10176
	v_mfma_f32_16x16x4_f32 v[208:211], v185, v253, v[208:211]
	v_mfma_f32_16x16x4_f32 v[212:215], v189, v253, v[212:215]
	v_mfma_f32_16x16x4_f32 v[216:219], v193, v253, v[216:219]
	v_mfma_f32_16x16x4_f32 v[220:223], v197, v253, v[220:223]
	v_mfma_f32_16x16x4_f32 v[248:251], v134, v252, v[72:75]
	v_mfma_f32_16x16x4_f32 v[248:251], v135, v253, v[248:251]
	s_waitcnt lgkmcnt(3)
	v_pk_mul_f32 v[208:209], v[208:209], v[140:141]
	v_pk_mul_f32 v[210:211], v[210:211], v[142:143]
	s_waitcnt lgkmcnt(2)
	v_pk_mul_f32 v[212:213], v[212:213], v[144:145]
	v_pk_mul_f32 v[214:215], v[214:215], v[146:147]
	s_waitcnt lgkmcnt(1)
	v_pk_mul_f32 v[216:217], v[216:217], v[148:149]
	v_pk_mul_f32 v[218:219], v[218:219], v[150:151]
	s_waitcnt lgkmcnt(0)
	v_pk_mul_f32 v[220:221], v[220:221], v[152:153]
	v_pk_mul_f32 v[222:223], v[222:223], v[154:155]
	s_mov_b64 exec, s[98:99]
	s_nop 0
	ds_write_b32 v231, v248 offset:6144
	ds_write_b32 v231, v249 offset:6400
	ds_write_b32 v231, v250 offset:6656
	ds_write_b32 v231, v251 offset:6912
	s_mov_b64 exec, -1
	s_branch .LBB0_655
.Lmy_f_hlp:
	s_setprio 3
	s_cmp_eq_u32 s65, 0
	s_cbranch_scc1 .Lmy_f_nofl
	v_subrev_u32_e32 v70, 16, v70
	v_add_u32_e32 v71, 16, v71
	s_and_b32 s96, s64, 0x800
	v_lshl_add_u32 v21, s96, 2, v68
	v_add_u32_e32 v21, 0xfffff000, v21
	v_cndmask_b32_e64 v76, v71, v70, s[4:5]
	ds_read_b128 v[72:75], v21
	v_ashrrev_i32_e64 v77, 31, v76
	v_lshl_add_u64 v[76:77], v[76:77], 0, s[40:41]
	v_lshlrev_b64 v[76:77], 12, v[76:77]
	v_lshl_add_u64 v[76:77], v[54:55], 0, v[76:77]
	s_waitcnt lgkmcnt(0)
	global_store_dwordx4 v[76:77], v[72:75], off
	v_add_u32_e32 v70, 16, v70
	v_subrev_u32_e32 v71, 16, v71

.Lmy_f_hl2:
	s_bfe_u32 s100, s62, 0x20006
	s_lshl_b32 s100, s100, 2
	s_add_i32 s101, s100, -16
	s_add_i32 s100, s100, -12
	s_cmp_lg_u32 s65, 0
	s_cbranch_scc1 .Lmy_f_nol2
	v_add_u32_e32 v70, s101, v70
	v_subrev_u32_e32 v71, s101, v71
	v_add_u32_e32 v21, 64, v70
	v_subrev_u32_e32 v26, 64, v71
	v_cndmask_b32_e64 v32, v26, v21, s[4:5]
	v_ashrrev_i32_e64 v33, 31, v32
	v_lshl_add_u64 v[44:45], v[32:33], 0, s[40:41]
	v_mad_u64_u32 v[46:47], s[96:97], v44, s56, v[50:51]
	v_mad_i32_i24 v47, v45, s56, v47
	v_mov_b32_e32 v166, v46
	v_mov_b32_e32 v167, v47
	global_load_dwordx2 v[26:27], v[46:47], off
	v_mov_b32_e32 v30, v20
	v_mov_b32_e32 v31, v20
	v_cmp_lt_i32_e64 s[96:97], 0, v32
	v_mov_b64_e32 v[28:29], v[30:31]
	s_and_saveexec_b64 s[24:25], s[96:97]
	s_cbranch_execz .Lmy_f_k659
	v_add_co_u32_e32 v28, vcc, 0xfffff000, v46
	s_nop 1
	v_addc_co_u32_e32 v29, vcc, -1, v47, vcc
	global_load_dwordx2 v[28:29], v[28:29], off offset:-2048

.Lmy_f_k669:
	s_or_b64 exec, exec, s[96:97]
	v_lshlrev_b64 v[44:45], 13, v[44:45]
	v_lshl_add_u64 v[44:45], v[52:53], 0, v[44:45]
	v_mov_b32_e32 v170, v44
	v_mov_b32_e64 v171, v45
	v_add_co_u32_e32 v46, vcc, 0x1000, v44
	s_nop 1
	v_addc_co_u32_e32 v47, vcc, 0, v45, vcc
	global_load_dwordx2 v[44:45], v[44:45], off
	s_nop 0
	global_load_dwordx2 v[46:47], v[46:47], off
	v_subrev_u32_e32 v70, s101, v70
	v_add_u32_e32 v71, s101, v71
	v_add_u32_e32 v70, s100, v70
	v_subrev_u32_e32 v71, s100, v71
	v_add_u32_e32 v21, 64, v70
	v_subrev_u32_e64 v140, 64, v71
	v_cndmask_b32_e64 v146, v140, v21, s[4:5]
	v_ashrrev_i32_e64 v147, 31, v146
	v_lshl_add_u64 v[158:159], v[146:147], 0, s[40:41]
	v_mad_u64_u32 v[160:161], s[96:97], v158, s56, v[50:51]
	v_mad_i32_i24 v161, v159, s56, v161
	v_mov_b32_e32 v174, v160
	v_mov_b32_e32 v175, v161
	global_load_dwordx2 v[140:141], v[160:161], off
	v_mov_b32_e32 v144, v20
	v_mov_b32_e32 v145, v20
	v_cmp_lt_i32_e64 s[96:97], 0, v146
	v_mov_b64_e32 v[142:143], v[144:145]
	s_and_saveexec_b64 s[24:25], s[96:97]
	s_cbranch_execz .Lmy_f_l659
	v_add_co_u32_e32 v142, vcc, 0xfffff000, v160
	s_nop 1
	v_addc_co_u32_e32 v143, vcc, -1, v161, vcc
	global_load_dwordx2 v[142:143], v[142:143], off offset:-2048

.Lmy_f_l669:
	s_or_b64 exec, exec, s[96:97]
	v_lshlrev_b64 v[158:159], 13, v[158:159]
	v_lshl_add_u64 v[158:159], v[52:53], 0, v[158:159]
	v_mov_b32_e32 v178, v158
	v_mov_b32_e64 v179, v159
	v_add_co_u32_e32 v160, vcc, 0x1000, v158
	s_nop 1
	v_addc_co_u32_e32 v161, vcc, 0, v159, vcc
	global_load_dwordx2 v[158:159], v[158:159], off
	s_nop 0
	global_load_dwordx2 v[160:161], v[160:161], off
	v_subrev_u32_e32 v70, s100, v70
	v_add_u32_e64 v71, s100, v71
	s_mov_b32 s96, 0xffffe000
	s_mov_b32 s97, -1
	v_lshl_add_u64 v[164:165], v[166:167], 0, s[96:97]
	v_lshl_add_u64 v[172:173], v[174:175], 0, s[96:97]
	s_mov_b32 s96, 0x2000
	s_mov_b32 s97, 0
	v_lshl_add_u64 v[168:169], v[166:167], 0, s[96:97]
	v_lshl_add_u64 v[176:177], v[174:175], 0, s[96:97]
	s_mov_b32 s96, 0x800
	v_lshl_add_u64 v[170:171], v[170:171], 0, s[96:97]
	v_lshl_add_u64 v[178:179], v[178:179], 0, s[96:97]
.Lmy_f_nol2:
	s_lshl_b32 s96, s101, 8
	v_add_u32_e32 v67, s96, v67
	s_andn2_b64 vcc, exec, s[50:51]
	s_cbranch_vccnz .LBB0_655
	s_waitcnt vmcnt(15)
	v_lshlrev_b32_e32 v72, 16, v28
	v_and_b32_e32 v73, 0xffff0000, v28
	v_lshlrev_b32_e64 v76, 16, v30
	v_and_b32_e32 v77, 0xffff0000, v30
	v_lshlrev_b32_e64 v74, 16, v26
	v_and_b32_e32 v75, 0xffff0000, v26
	v_pk_add_f32 v[72:73], v[72:73], v[76:77]
	s_waitcnt vmcnt(13)
	v_lshlrev_b32_e32 v78, 16, v42
	v_pk_fma_f32 v[72:73], v[72:73], 0.5, v[74:75] op_sel_hi:[1,0,1] neg_lo:[0,0,1] neg_hi:[0,0,1]
	v_and_b32_e32 v79, 0xffff0000, v42
	v_pk_fma_f32 v[72:73], v[0:1], v[72:73], v[74:75]
	v_lshlrev_b32_e64 v74, 16, v40
	v_and_b32_e32 v75, 0xffff0000, v40
	v_lshlrev_b32_e64 v76, 16, v38
	v_and_b32_e32 v77, 0xffff0000, v38
	v_pk_add_f32 v[74:75], v[74:75], v[78:79]
	s_waitcnt vmcnt(12)
	v_cvt_f32_f16_e32 v21, v44
	v_pk_fma_f32 v[74:75], v[74:75], 0.5, v[76:77] op_sel_hi:[1,0,1] neg_lo:[0,0,1] neg_hi:[0,0,1]
	v_lshlrev_b32_e64 v80, 16, v31
	v_pk_fma_f32 v[76:77], v[8:9], v[74:75], v[76:77]
	v_lshlrev_b32_e64 v74, 16, v29
	v_and_b32_e32 v75, 0xffff0000, v29
	v_and_b32_e32 v81, 0xffff0000, v31
	v_lshlrev_b32_e64 v78, 16, v27
	v_and_b32_e32 v79, 0xffff0000, v27
	v_pk_add_f32 v[74:75], v[74:75], v[80:81]
	v_cvt_f32_f16_sdwa v84, v44 dst_sel:DWORD dst_unused:UNUSED_PAD src0_sel:WORD_1
	v_pk_fma_f32 v[74:75], v[74:75], 0.5, v[78:79] op_sel_hi:[1,0,1] neg_lo:[0,0,1] neg_hi:[0,0,1]
	v_lshlrev_b32_e64 v82, 16, v43
	v_pk_fma_f32 v[74:75], v[2:3], v[74:75], v[78:79]
	v_lshlrev_b32_e64 v78, 16, v41
	v_and_b32_e32 v79, 0xffff0000, v41
	v_and_b32_e32 v83, 0xffff0000, v43
	v_cvt_f32_f16_e32 v88, v45
	v_lshlrev_b32_e32 v80, 16, v39
	v_and_b32_e32 v81, 0xffff0000, v39
	v_pk_add_f32 v[78:79], v[78:79], v[82:83]
	v_mul_f32_e32 v21, 0xbf1b4598, v21
	v_pk_fma_f32 v[78:79], v[78:79], 0.5, v[80:81] op_sel_hi:[1,0,1] neg_lo:[0,0,1] neg_hi:[0,0,1]
	v_mul_f32_e32 v21, 0x3fb8aa3b, v21
	v_cvt_f32_f16_sdwa v89, v45 dst_sel:DWORD dst_unused:UNUSED_PAD src0_sel:WORD_1
	v_pk_fma_f32 v[78:79], v[10:11], v[78:79], v[80:81]
	v_exp_f32_e64 v80, v21
	v_mul_f32_e32 v21, 0xbf1b4598, v84
	v_mul_f32_e32 v21, 0x3fb8aa3b, v21
	v_lshlrev_b32_e64 v82, 16, v34
	v_and_b32_e32 v83, 0xffff0000, v34
	v_lshlrev_b32_e64 v86, 16, v36
	v_and_b32_e32 v87, 0xffff0000, v36
	v_exp_f32_e32 v81, v21
	v_lshlrev_b32_e32 v84, 16, v32
	v_and_b32_e32 v85, 0xffff0000, v32
	v_pk_add_f32 v[82:83], v[82:83], v[86:87]
	v_mul_f32_e32 v21, 0xbf1b4598, v88
	v_pk_fma_f32 v[82:83], v[82:83], 0.5, v[84:85] op_sel_hi:[1,0,1] neg_lo:[0,0,1] neg_hi:[0,0,1]
	v_mul_f32_e32 v21, 0x3fb8aa3b, v21
	v_pk_fma_f32 v[96:97], v[4:5], v[82:83], v[84:85]
	v_exp_f32_e64 v82, v21
	v_mul_f32_e32 v21, 0xbf1b4598, v89
	v_lshlrev_b32_e64 v84, 16, v35
	v_and_b32_e32 v85, 0xffff0000, v35
	v_lshlrev_b32_e64 v88, 16, v37
	v_and_b32_e32 v89, 0xffff0000, v37
	v_lshlrev_b32_e64 v86, 16, v33
	v_and_b32_e32 v87, 0xffff0000, v33
	v_pk_add_f32 v[84:85], v[84:85], v[88:89]
	s_waitcnt vmcnt(11)
	v_cvt_f32_f16_sdwa v93, v46 dst_sel:DWORD dst_unused:UNUSED_PAD src0_sel:WORD_1
	v_pk_fma_f32 v[84:85], v[84:85], 0.5, v[86:87] op_sel_hi:[1,0,1] neg_lo:[0,0,1] neg_hi:[0,0,1]
	v_cvt_f32_f16_e32 v92, v46
	v_pk_fma_f32 v[94:95], v[6:7], v[84:85], v[86:87]
	v_pk_mul_f32 v[84:85], v[12:13], v[96:97]
	v_pk_mul_f32 v[88:89], v[14:15], v[94:95]
	v_pk_mul_f32 v[86:87], v[84:85], v[84:85]
	v_pk_mul_f32 v[90:91], v[88:89], v[88:89]
	v_add_f32_e32 v83, v86, v87
	v_add_f32_e32 v83, v90, v83
	v_add_f32_e64 v83, v91, v83
	v_cvt_f32_f16_sdwa v99, v47 dst_sel:DWORD dst_unused:UNUSED_PAD src0_sel:WORD_1
	v_cvt_f32_f16_e32 v98, v47
	v_add_f32_dpp v83, v83, v83 quad_perm:[1,0,3,2] row_mask:0xf bank_mask:0xf bound_ctrl:1
	v_mul_f32_e32 v21, 0x3fb8aa3b, v21
	s_bitcmp1_b32 s22, 0
	v_add_f32_dpp v83, v83, v83 quad_perm:[2,3,0,1] row_mask:0xf bank_mask:0xf bound_ctrl:1
	s_cselect_b32 s23, 0x2000, 0
	s_nop 0
	v_add_f32_dpp v83, v83, v83 row_half_mirror row_mask:0xf bank_mask:0xf bound_ctrl:1
	s_nop 1
	v_add_f32_dpp v83, v83, v83 row_mirror row_mask:0xf bank_mask:0xf bound_ctrl:1
	v_max_f32_e32 v83, 0x179abe15, v83
	v_rsq_f32_e32 v86, v83
	v_exp_f32_e32 v83, v21
	v_add_u32_e64 v21, s23, v67
	v_pk_mul_f32 v[90:91], v[84:85], v[86:87] op_sel_hi:[1,0]
	v_pk_mul_f32 v[100:101], v[88:89], v[86:87] op_sel_hi:[1,0]
	v_xor_b32_e32 v85, 0x80000000, v91
	v_xor_b32_e32 v84, 0x80000000, v90
	v_pk_mul_f32 v[88:89], v[90:91], v[92:93]
	v_pk_mul_f32 v[90:91], v[100:101], v[98:99]
	v_pk_add_f32 v[92:93], v[92:93], -1.0 op_sel_hi:[1,0]
	v_pk_add_f32 v[98:99], v[98:99], -1.0 op_sel_hi:[1,0]
	v_pk_fma_f32 v[92:93], v[16:17], v[92:93], 1.0 op_sel_hi:[1,1,0]
	v_pk_fma_f32 v[98:99], v[18:19], v[98:99], 1.0 op_sel_hi:[1,1,0]
	v_xor_b32_e32 v86, 0x80000000, v100
	v_xor_b32_e32 v87, 0x80000000, v101
	v_pk_mul_f32 v[94:95], v[94:95], v[98:99]
	v_pk_mul_f32 v[92:93], v[96:97], v[92:93]
	ds_write_b128 v67, v[80:83]
	ds_write_b128 v67, v[84:87] offset:8192
	ds_write_b128 v67, v[88:91] offset:16384
	ds_write_b128 v67, v[92:95] offset:24576
	ds_write_b128 v67, v[72:75] offset:32768
	ds_write_b128 v21, v[76:79] offset:40960
	v_add_u32_e32 v67, 0x400, v67
	s_waitcnt vmcnt(0)
	v_lshlrev_b32_e32 v72, 16, v142
	v_and_b32_e32 v73, 0xffff0000, v142
	v_lshlrev_b32_e64 v76, 16, v144
	v_and_b32_e32 v77, 0xffff0000, v144
	v_lshlrev_b32_e64 v74, 16, v140
	v_and_b32_e32 v75, 0xffff0000, v140
	v_pk_add_f32 v[72:73], v[72:73], v[76:77]
	s_waitcnt vmcnt(2)
	v_lshlrev_b32_e32 v78, 16, v156
	v_pk_fma_f32 v[72:73], v[72:73], 0.5, v[74:75] op_sel_hi:[1,0,1] neg_lo:[0,0,1] neg_hi:[0,0,1]
	v_and_b32_e32 v79, 0xffff0000, v156
	v_pk_fma_f32 v[72:73], v[0:1], v[72:73], v[74:75]
	v_lshlrev_b32_e64 v74, 16, v154
	v_and_b32_e32 v75, 0xffff0000, v154
	v_lshlrev_b32_e64 v76, 16, v152
	v_and_b32_e32 v77, 0xffff0000, v152
	v_pk_add_f32 v[74:75], v[74:75], v[78:79]
	s_waitcnt vmcnt(1)
	v_cvt_f32_f16_e32 v21, v158
	v_pk_fma_f32 v[74:75], v[74:75], 0.5, v[76:77] op_sel_hi:[1,0,1] neg_lo:[0,0,1] neg_hi:[0,0,1]
	v_lshlrev_b32_e64 v80, 16, v145
	v_pk_fma_f32 v[76:77], v[8:9], v[74:75], v[76:77]
	v_lshlrev_b32_e64 v74, 16, v143
	v_and_b32_e32 v75, 0xffff0000, v143
	v_and_b32_e32 v81, 0xffff0000, v145
	v_lshlrev_b32_e64 v78, 16, v141
	v_and_b32_e32 v79, 0xffff0000, v141
	v_pk_add_f32 v[74:75], v[74:75], v[80:81]
	v_cvt_f32_f16_sdwa v84, v158 dst_sel:DWORD dst_unused:UNUSED_PAD src0_sel:WORD_1
	v_pk_fma_f32 v[74:75], v[74:75], 0.5, v[78:79] op_sel_hi:[1,0,1] neg_lo:[0,0,1] neg_hi:[0,0,1]
	v_lshlrev_b32_e64 v82, 16, v157
	v_pk_fma_f32 v[74:75], v[2:3], v[74:75], v[78:79]
	v_lshlrev_b32_e64 v78, 16, v155
	v_and_b32_e32 v79, 0xffff0000, v155
	v_and_b32_e32 v83, 0xffff0000, v157
	v_cvt_f32_f16_e32 v88, v159
	v_lshlrev_b32_e32 v80, 16, v153
	v_and_b32_e32 v81, 0xffff0000, v153
	v_pk_add_f32 v[78:79], v[78:79], v[82:83]
	v_mul_f32_e32 v21, 0xbf1b4598, v21
	v_pk_fma_f32 v[78:79], v[78:79], 0.5, v[80:81] op_sel_hi:[1,0,1] neg_lo:[0,0,1] neg_hi:[0,0,1]
	v_mul_f32_e32 v21, 0x3fb8aa3b, v21
	v_cvt_f32_f16_sdwa v89, v159 dst_sel:DWORD dst_unused:UNUSED_PAD src0_sel:WORD_1
	v_pk_fma_f32 v[78:79], v[10:11], v[78:79], v[80:81]
	v_exp_f32_e64 v80, v21
	v_mul_f32_e32 v21, 0xbf1b4598, v84
	v_mul_f32_e32 v21, 0x3fb8aa3b, v21
	v_lshlrev_b32_e64 v82, 16, v148
	v_and_b32_e32 v83, 0xffff0000, v148
	v_lshlrev_b32_e64 v86, 16, v150
	v_and_b32_e32 v87, 0xffff0000, v150
	v_exp_f32_e32 v81, v21
	v_lshlrev_b32_e32 v84, 16, v146
	v_and_b32_e32 v85, 0xffff0000, v146
	v_pk_add_f32 v[82:83], v[82:83], v[86:87]
	v_mul_f32_e32 v21, 0xbf1b4598, v88
	v_pk_fma_f32 v[82:83], v[82:83], 0.5, v[84:85] op_sel_hi:[1,0,1] neg_lo:[0,0,1] neg_hi:[0,0,1]
	v_mul_f32_e32 v21, 0x3fb8aa3b, v21
	v_pk_fma_f32 v[96:97], v[4:5], v[82:83], v[84:85]
	v_exp_f32_e64 v82, v21
	v_mul_f32_e32 v21, 0xbf1b4598, v89
	v_lshlrev_b32_e64 v84, 16, v149
	v_and_b32_e32 v85, 0xffff0000, v149
	v_lshlrev_b32_e64 v88, 16, v151
	v_and_b32_e32 v89, 0xffff0000, v151
	v_lshlrev_b32_e64 v86, 16, v147
	v_and_b32_e32 v87, 0xffff0000, v147
	v_pk_add_f32 v[84:85], v[84:85], v[88:89]
	s_waitcnt vmcnt(0)
	v_cvt_f32_f16_sdwa v93, v160 dst_sel:DWORD dst_unused:UNUSED_PAD src0_sel:WORD_1
	v_pk_fma_f32 v[84:85], v[84:85], 0.5, v[86:87] op_sel_hi:[1,0,1] neg_lo:[0,0,1] neg_hi:[0,0,1]
	v_cvt_f32_f16_e32 v92, v160
	v_pk_fma_f32 v[94:95], v[6:7], v[84:85], v[86:87]
	v_pk_mul_f32 v[84:85], v[12:13], v[96:97]
	v_pk_mul_f32 v[88:89], v[14:15], v[94:95]
	v_pk_mul_f32 v[86:87], v[84:85], v[84:85]
	v_pk_mul_f32 v[90:91], v[88:89], v[88:89]
	v_add_f32_e32 v83, v86, v87
	v_add_f32_e32 v83, v90, v83
	v_add_f32_e64 v83, v91, v83
	v_cvt_f32_f16_sdwa v99, v161 dst_sel:DWORD dst_unused:UNUSED_PAD src0_sel:WORD_1
	v_cvt_f32_f16_e32 v98, v161
	v_add_f32_dpp v83, v83, v83 quad_perm:[1,0,3,2] row_mask:0xf bank_mask:0xf bound_ctrl:1
	v_mul_f32_e32 v21, 0x3fb8aa3b, v21
	s_bitcmp1_b32 s22, 0
	v_add_f32_dpp v83, v83, v83 quad_perm:[2,3,0,1] row_mask:0xf bank_mask:0xf bound_ctrl:1
	s_cselect_b32 s23, 0x2000, 0
	s_nop 0
	v_add_f32_dpp v83, v83, v83 row_half_mirror row_mask:0xf bank_mask:0xf bound_ctrl:1
	s_nop 1
	v_add_f32_dpp v83, v83, v83 row_mirror row_mask:0xf bank_mask:0xf bound_ctrl:1
	v_max_f32_e32 v83, 0x179abe15, v83
	v_rsq_f32_e32 v86, v83
	v_exp_f32_e32 v83, v21
	v_add_u32_e64 v21, s23, v67
	v_pk_mul_f32 v[90:91], v[84:85], v[86:87] op_sel_hi:[1,0]
	v_pk_mul_f32 v[100:101], v[88:89], v[86:87] op_sel_hi:[1,0]
	v_xor_b32_e32 v85, 0x80000000, v91
	v_xor_b32_e32 v84, 0x80000000, v90
	v_pk_mul_f32 v[88:89], v[90:91], v[92:93]
	v_pk_mul_f32 v[90:91], v[100:101], v[98:99]
	v_pk_add_f32 v[92:93], v[92:93], -1.0 op_sel_hi:[1,0]
	v_pk_add_f32 v[98:99], v[98:99], -1.0 op_sel_hi:[1,0]
	v_pk_fma_f32 v[92:93], v[16:17], v[92:93], 1.0 op_sel_hi:[1,1,0]
	v_pk_fma_f32 v[98:99], v[18:19], v[98:99], 1.0 op_sel_hi:[1,1,0]
	v_xor_b32_e32 v86, 0x80000000, v100
	v_xor_b32_e32 v87, 0x80000000, v101
	v_pk_mul_f32 v[94:95], v[94:95], v[98:99]
	v_pk_mul_f32 v[92:93], v[96:97], v[92:93]
	ds_write_b128 v67, v[80:83]
	ds_write_b128 v67, v[84:87] offset:8192
	ds_write_b128 v67, v[88:91] offset:16384
	ds_write_b128 v67, v[92:95] offset:24576
	ds_write_b128 v67, v[72:75] offset:32768
	ds_write_b128 v21, v[76:79] offset:40960
	s_lshl_b32 s96, s100, 8
	v_subrev_u32_e32 v67, s96, v67
	s_cmp_gt_u32 s65, 61
	s_cbranch_scc1 .Lmy_f_nol34
	s_cmp_eq_u32 s65, 61
	s_cbranch_scc1 .Lmy_f_slow34
	s_cmp_lg_u32 s4, 0
	s_mov_b32 s100, 0xfffd0000
	s_cselect_b32 s100, 0x30000, s100
	s_cselect_b32 s101, 0, -1
	s_mov_b32 s96, 0xfffc0000
	s_cselect_b32 s96, 0x40000, s96
	s_cselect_b32 s97, 0, -1
	v_lshl_add_u64 v[166:167], v[166:167], 0, s[100:101]
	v_lshl_add_u64 v[164:165], v[164:165], 0, s[100:101]
	v_lshl_add_u64 v[168:169], v[168:169], 0, s[100:101]
	v_lshl_add_u64 v[170:171], v[170:171], 0, s[96:97]
	global_load_dwordx2 v[26:27], v[166:167], off
	global_load_dwordx2 v[28:29], v[164:165], off offset:2048
	global_load_dwordx2 v[30:31], v[168:169], off offset:-2048
	global_load_dwordx2 v[32:33], v[166:167], off offset:2048
	global_load_dwordx2 v[34:35], v[166:167], off offset:-4096
	global_load_dwordx2 v[36:37], v[168:169], off
	global_load_dwordx2 v[38:39], v[168:169], off offset:-4096
	global_load_dwordx2 v[40:41], v[166:167], off offset:-2048
	global_load_dwordx2 v[42:43], v[168:169], off offset:2048
	global_load_dwordx2 v[44:45], v[170:171], off offset:-2048
	global_load_dwordx2 v[46:47], v[170:171], off offset:2048
	v_lshl_add_u64 v[174:175], v[174:175], 0, s[100:101]
	v_lshl_add_u64 v[172:173], v[172:173], 0, s[100:101]
	v_lshl_add_u64 v[176:177], v[176:177], 0, s[100:101]
	v_lshl_add_u64 v[178:179], v[178:179], 0, s[96:97]
	global_load_dwordx2 v[140:141], v[174:175], off
	global_load_dwordx2 v[142:143], v[172:173], off offset:2048
	global_load_dwordx2 v[144:145], v[176:177], off offset:-2048
	global_load_dwordx2 v[146:147], v[174:175], off offset:2048
	global_load_dwordx2 v[148:149], v[174:175], off offset:-4096
	global_load_dwordx2 v[150:151], v[176:177], off
	global_load_dwordx2 v[152:153], v[176:177], off offset:-4096
	global_load_dwordx2 v[154:155], v[174:175], off offset:-2048
	global_load_dwordx2 v[156:157], v[176:177], off offset:2048
	global_load_dwordx2 v[158:159], v[178:179], off offset:-2048
	global_load_dwordx2 v[160:161], v[178:179], off offset:2048
	s_branch .Lmy_f_nol34
.Lmy_f_slow34:
	s_add_i32 s101, s101, 32
	s_add_i32 s100, s100, 32
	v_add_u32_e32 v70, s101, v70
	v_subrev_u32_e32 v71, s101, v71
	v_add_u32_e32 v21, 64, v70
	v_subrev_u32_e32 v26, 64, v71
	v_cndmask_b32_e64 v32, v26, v21, s[4:5]
	v_ashrrev_i32_e64 v33, 31, v32
	v_lshl_add_u64 v[44:45], v[32:33], 0, s[40:41]
	v_mad_u64_u32 v[46:47], s[96:97], v44, s56, v[50:51]
	v_mad_i32_i24 v47, v45, s56, v47
	global_load_dwordx2 v[26:27], v[46:47], off
	v_mov_b32_e32 v30, v20
	v_mov_b32_e32 v31, v20
	v_cmp_lt_i32_e64 s[96:97], 0, v32
	v_mov_b64_e32 v[28:29], v[30:31]
	s_and_saveexec_b64 s[24:25], s[96:97]
	s_cbranch_execz .Lmy_f_m659
	v_add_co_u32_e32 v28, vcc, 0xfffff000, v46
	s_nop 1
	v_addc_co_u32_e32 v29, vcc, -1, v47, vcc
	global_load_dwordx2 v[28:29], v[28:29], off offset:-2048

.Lmy_f_m669:
	s_or_b64 exec, exec, s[96:97]
	v_lshlrev_b64 v[44:45], 13, v[44:45]
	v_lshl_add_u64 v[44:45], v[52:53], 0, v[44:45]
	v_add_co_u32_e32 v46, vcc, 0x1000, v44
	s_nop 1
	v_addc_co_u32_e32 v47, vcc, 0, v45, vcc
	global_load_dwordx2 v[44:45], v[44:45], off
	s_nop 0
	global_load_dwordx2 v[46:47], v[46:47], off
	v_subrev_u32_e32 v70, s101, v70
	v_add_u32_e32 v71, s101, v71
	v_add_u32_e32 v70, s100, v70
	v_subrev_u32_e32 v71, s100, v71
	v_add_u32_e32 v21, 64, v70
	v_subrev_u32_e32 v140, 64, v71
	v_cndmask_b32_e64 v146, v140, v21, s[4:5]
	v_ashrrev_i32_e64 v147, 31, v146
	v_lshl_add_u64 v[158:159], v[146:147], 0, s[40:41]
	v_mad_u64_u32 v[160:161], s[96:97], v158, s56, v[50:51]
	v_mad_i32_i24 v161, v159, s56, v161
	global_load_dwordx2 v[140:141], v[160:161], off
	v_mov_b32_e32 v144, v20
	v_mov_b32_e32 v145, v20
	v_cmp_lt_i32_e64 s[96:97], 0, v146
	v_mov_b64_e32 v[142:143], v[144:145]
	s_and_saveexec_b64 s[24:25], s[96:97]
	s_cbranch_execz .Lmy_f_n659
	v_add_co_u32_e32 v142, vcc, 0xfffff000, v160
	s_nop 1
	v_addc_co_u32_e32 v143, vcc, -1, v161, vcc
	global_load_dwordx2 v[142:143], v[142:143], off offset:-2048

.Lmy_f_nol34:
	s_waitcnt lgkmcnt(0)
	s_bfe_u32 s96, s62, 0x20006
	s_lshl_b32 s100, s96, 11
	v_lshl_add_u32 v72, v224, 2, s100
	s_and_b32 s97, s96, 1
	s_mul_i32 s97, s97, 0x2700
	s_mov_b32 s101, 0x1c000
	s_mov_b32 s100, 0x6100
	s_bitcmp0_b32 s65, 0
	s_cselect_b32 s101, 0xe000, s101
	s_cselect_b32 s100, 0x4e00, s100
	s_cmp_gt_u32 s96, 1
	s_cselect_b32 s100, s100, 0
	s_add_i32 s97, s97, s101
	s_add_i32 s97, s97, s100
	ds_read_b32 v80, v72
	ds_read_b32 v81, v72 offset:256
	ds_read_b32 v82, v72 offset:512
	ds_read_b32 v83, v72 offset:768
	ds_read_b32 v84, v72 offset:1024
	ds_read_b32 v85, v72 offset:1280
	ds_read_b32 v86, v72 offset:1536
	ds_read_b32 v87, v72 offset:1792
	ds_read_b32 v88, v72 offset:8192
	ds_read_b32 v89, v72 offset:8448
	ds_read_b32 v90, v72 offset:8704
	ds_read_b32 v91, v72 offset:8960
	ds_read_b32 v92, v72 offset:9216
	ds_read_b32 v93, v72 offset:9472
	ds_read_b32 v94, v72 offset:9728
	ds_read_b32 v95, v72 offset:9984
	ds_read_b32 v96, v72 offset:32768
	ds_read_b32 v97, v72 offset:33024
	ds_read_b32 v98, v72 offset:33280
	ds_read_b32 v99, v72 offset:33536
	ds_read_b32 v100, v72 offset:33792
	ds_read_b32 v101, v72 offset:34048
	ds_read_b32 v102, v72 offset:34304
	ds_read_b32 v103, v72 offset:34560
	v_and_b32_e64 v74, 3, v224
	v_bfe_u32 v75, v224, 2, 2
	v_lshrrev_b32_e32 v76, 4, v224
	v_lshlrev_b32_e32 v74, 2, v74
	v_lshl_add_u32 v74, v75, 8, v74
	v_lshl_add_u32 v74, v76, 10, v74
	s_add_i32 s100, s97, 0x0
	v_add_u32_e32 v74, s100, v74
	v_xor_b32_e32 v76, 0, v75
	v_xor_b32_e32 v77, 1, v75
	v_xor_b32_e32 v78, 2, v75
	v_xor_b32_e32 v79, 3, v75
	v_lshl_add_u32 v76, v76, 4, v74
	v_lshl_add_u32 v77, v77, 4, v74
	v_lshl_add_u32 v78, v78, 4, v74
	v_lshl_add_u32 v79, v79, 4, v74
	s_waitcnt lgkmcnt(15)
	v_mov_b32_e32 v104, v80
	v_mul_f32_e32 v105, v104, v81
	v_mul_f32_e32 v106, v105, v82
	v_mul_f32_e32 v107, v106, v83
	v_mul_f32_e32 v108, v107, v84
	v_mul_f32_e32 v109, v108, v85
	v_mul_f32_e32 v110, v109, v86
	v_mul_f32_e32 v111, v110, v87
	v_mov_b32_e32 v112, v88
	s_waitcnt lgkmcnt(14)
	v_mul_f32_e32 v113, v104, v89
	s_waitcnt lgkmcnt(13)
	v_mul_f32_e32 v114, v105, v90
	s_waitcnt lgkmcnt(12)
	v_mul_f32_e32 v115, v106, v91
	s_waitcnt lgkmcnt(11)
	v_mul_f32_e32 v116, v107, v92
	s_waitcnt lgkmcnt(10)
	v_mul_f32_e32 v117, v108, v93
	s_waitcnt lgkmcnt(9)
	v_mul_f32_e32 v118, v109, v94
	s_waitcnt lgkmcnt(8)
	v_mul_f32_e32 v119, v110, v95
	s_waitcnt lgkmcnt(7)
	v_mul_f32_e32 v120, v104, v96
	s_waitcnt lgkmcnt(6)
	v_mul_f32_e32 v121, v105, v97
	s_waitcnt lgkmcnt(5)
	v_mul_f32_e32 v122, v106, v98
	s_waitcnt lgkmcnt(4)
	v_mul_f32_e32 v123, v107, v99
	s_waitcnt lgkmcnt(3)
	v_mul_f32_e32 v124, v108, v100
	s_waitcnt lgkmcnt(2)
	v_mul_f32_e32 v125, v109, v101
	s_waitcnt lgkmcnt(1)
	v_mul_f32_e32 v126, v110, v102
	s_waitcnt lgkmcnt(0)
	v_mul_f32_e32 v127, v111, v103
	ds_write_b32 v76, v112
	ds_write_b32 v77, v113
	ds_write_b32 v78, v114
	ds_write_b32 v79, v115
	ds_write_b32 v76, v116 offset:64
	ds_write_b32 v77, v117 offset:64
	ds_write_b32 v78, v118 offset:64
	ds_write_b32 v79, v119 offset:64
	ds_write_b32 v76, v120 offset:128
	ds_write_b32 v77, v121 offset:128
	ds_write_b32 v78, v122 offset:128
	ds_write_b32 v79, v123 offset:128
	ds_write_b32 v76, v124 offset:192
	ds_write_b32 v77, v125 offset:192
	ds_write_b32 v78, v126 offset:192
	ds_write_b32 v79, v127 offset:192
.Lmy_ck_drB_h:
	s_waitcnt lgkmcnt(0)
	ds_read_b32 v88, v72 offset:16384
	ds_read_b32 v89, v72 offset:16640
	ds_read_b32 v90, v72 offset:16896
	ds_read_b32 v91, v72 offset:17152
	ds_read_b32 v92, v72 offset:17408
	ds_read_b32 v93, v72 offset:17664
	ds_read_b32 v94, v72 offset:17920
	ds_read_b32 v95, v72 offset:18176
	ds_read_b32 v96, v72 offset:24576
	ds_read_b32 v97, v72 offset:24832
	ds_read_b32 v98, v72 offset:25088
	ds_read_b32 v99, v72 offset:25344
	ds_read_b32 v100, v72 offset:25600
	ds_read_b32 v101, v72 offset:25856
	ds_read_b32 v102, v72 offset:26112
	ds_read_b32 v103, v72 offset:26368
	v_and_b32_e32 v74, 15, v224
	v_lshrrev_b32_e32 v76, 4, v224
	v_lshlrev_b32_e32 v74, 4, v74
	v_lshl_add_u32 v74, v76, 10, v74
	s_add_i32 s101, s97, 0x1000
	v_add_u32_e64 v74, s101, v74
	s_add_i32 s101, s97, 0x2000
	v_lshl_add_u32 v75, v224, 2, s101
	v_mov_b32_e32 v104, v80
	v_mul_f32_e32 v105, v104, v81
	v_mul_f32_e32 v106, v105, v82
	v_mul_f32_e32 v107, v106, v83
	v_mul_f32_e32 v108, v107, v84
	v_mul_f32_e32 v109, v108, v85
	v_mul_f32_e32 v110, v109, v86
	v_mul_f32_e32 v111, v110, v87
	v_rcp_f32_e32 v112, v104
	v_rcp_f32_e32 v113, v105
	v_rcp_f32_e32 v114, v106
	v_rcp_f32_e32 v115, v107
	v_rcp_f32_e32 v116, v108
	v_rcp_f32_e32 v117, v109
	v_rcp_f32_e32 v118, v110
	v_rcp_f32_e32 v119, v111
	s_waitcnt lgkmcnt(7)
	v_mul_f32_e32 v120, v112, v96
	s_waitcnt lgkmcnt(6)
	v_mul_f32_e32 v121, v113, v97
	s_waitcnt lgkmcnt(5)
	v_mul_f32_e32 v122, v114, v98
	s_waitcnt lgkmcnt(4)
	v_mul_f32_e32 v123, v115, v99
	s_waitcnt lgkmcnt(3)
	v_mul_f32_e32 v124, v116, v100
	s_waitcnt lgkmcnt(2)
	v_mul_f32_e32 v125, v117, v101
	s_waitcnt lgkmcnt(1)
	v_mul_f32_e32 v126, v118, v102
	s_waitcnt lgkmcnt(0)
	v_mul_f32_e32 v127, v119, v103
	v_mul_f32_e32 v112, v112, v88
	v_mul_f32_e32 v113, v113, v89
	v_mul_f32_e32 v114, v114, v90
	v_mul_f32_e32 v115, v115, v91
	v_mul_f32_e32 v116, v116, v92
	v_mul_f32_e32 v117, v117, v93
	v_mul_f32_e32 v118, v118, v94
	v_mul_f32_e32 v119, v119, v95
	ds_write_b128 v74, v[112:115]
	ds_write_b128 v74, v[116:119] offset:256
	ds_write_b128 v74, v[120:123] offset:512
	ds_write_b128 v74, v[124:127] offset:768
	ds_write_b32 v75, v111
.Lmy_ck_drE_h:
	s_waitcnt lgkmcnt(0)
	s_bfe_u32 s96, s62, 0x20006
	s_and_b32 s97, s96, 1
	s_mul_i32 s97, s97, 0x2700
	s_mov_b32 s101, 0x1c000
	s_mov_b32 s100, 0x6100
	s_bitcmp0_b32 s65, 0
	s_cselect_b32 s101, 0xe000, s101
	s_cselect_b32 s100, 0x4e00, s100
	s_cmp_gt_u32 s96, 1
	s_cselect_b32 s100, s100, 0
	s_add_i32 s97, s97, s101
	s_add_i32 s97, s97, s100
	s_mov_b32 s96, s97
	v_and_b32_e32 v72, 3, v233
	v_lshrrev_b32_e32 v73, 2, v233
	v_lshlrev_b32_e64 v72, 2, v72
	v_lshl_add_u32 v72, v73, 8, v72
	v_lshl_add_u32 v72, v234, 6, v72
	s_add_i32 s97, s96, 0x1000
	v_add_u32_e32 v78, s97, v72
	v_xor_b32_e32 v79, v224, v234
	v_lshl_add_u32 v79, v79, 4, s96
	ds_read_b128 v[96:99], v79
	ds_read_b128 v[100:103], v79 offset:1024
	ds_read_b128 v[104:107], v79 offset:2048
	ds_read_b128 v[108:111], v79 offset:3072
	ds_read_b32 v80, v78
	ds_read_b32 v81, v78 offset:16
	ds_read_b32 v82, v78 offset:32
	ds_read_b32 v83, v78 offset:48
	ds_read_b32 v84, v78 offset:1024
	ds_read_b32 v85, v78 offset:1040
	ds_read_b32 v86, v78 offset:1056
	ds_read_b32 v87, v78 offset:1072
	ds_read_b32 v88, v78 offset:2048
	ds_read_b32 v89, v78 offset:2064
	ds_read_b32 v90, v78 offset:2080
	ds_read_b32 v91, v78 offset:2096
	ds_read_b32 v92, v78 offset:3072
	ds_read_b32 v93, v78 offset:3088
	ds_read_b32 v94, v78 offset:3104
	ds_read_b32 v95, v78 offset:3120
	v_lshl_add_u32 v74, v224, 2, s96
	ds_write_b32 v74, v235 offset:9728
	v_add_u32_e32 v75, -1, v233
	v_mov_b32_e32 v76, -1
	v_cndmask_b32_e64 v75, v76, v75, s[98:99]
	v_cmp_lt_u32_e64 s[100:101], 7, v233
	v_add_u32_e32 v76, -8, v233
	v_and_b32_e32 v77, 1, v234
	v_cndmask_b32_e64 v75, v75, v76, s[100:101]
	v_lshlrev_b32_e32 v77, 2, v77
	v_sub_u32_e32 v76, v75, v77
	v_lshlrev_b32_e32 v77, 2, v234
	v_sub_u32_e32 v77, v233, v77
	v_add_u32_e32 v77, -1, v77
	s_waitcnt lgkmcnt(15)
	v_mfma_f32_16x16x4_f32 v[244:247], v80, v96, 0
	v_mfma_f32_16x16x4_f32 v[240:243], v81, v97, 0
	s_waitcnt lgkmcnt(14)
	v_mfma_f32_16x16x4_f32 v[244:247], v82, v98, v[244:247]
	s_waitcnt lgkmcnt(13)
	v_mfma_f32_16x16x4_f32 v[240:243], v83, v99, v[240:243]
	s_waitcnt lgkmcnt(12)
	v_mfma_f32_16x16x4_f32 v[244:247], v84, v100, v[244:247]
	s_waitcnt lgkmcnt(11)
	v_mfma_f32_16x16x4_f32 v[240:243], v85, v101, v[240:243]
	s_waitcnt lgkmcnt(10)
	v_mfma_f32_16x16x4_f32 v[244:247], v86, v102, v[244:247]
	s_waitcnt lgkmcnt(9)
	v_mfma_f32_16x16x4_f32 v[240:243], v87, v103, v[240:243]
	s_waitcnt lgkmcnt(8)
	v_mfma_f32_16x16x4_f32 v[244:247], v88, v104, v[244:247]
	s_waitcnt lgkmcnt(7)
	v_mfma_f32_16x16x4_f32 v[240:243], v89, v105, v[240:243]
	s_waitcnt lgkmcnt(6)
	v_mfma_f32_16x16x4_f32 v[244:247], v90, v106, v[244:247]
	s_waitcnt lgkmcnt(5)
	v_mfma_f32_16x16x4_f32 v[240:243], v91, v107, v[240:243]
	s_waitcnt lgkmcnt(4)
	v_mfma_f32_16x16x4_f32 v[244:247], v92, v108, v[244:247]
	s_waitcnt lgkmcnt(3)
	v_mfma_f32_16x16x4_f32 v[240:243], v93, v109, v[240:243]
	s_waitcnt lgkmcnt(2)
	v_mfma_f32_16x16x4_f32 v[244:247], v94, v110, v[244:247]
	s_waitcnt lgkmcnt(1)
	v_mfma_f32_16x16x4_f32 v[240:243], v95, v111, v[240:243]
	s_nop 9
	v_add_f32_e32 v244, v244, v240
	v_add_f32_e32 v245, v245, v241
	v_add_f32_e32 v246, v246, v242
	v_add_f32_e64 v247, v247, v243
	v_cmp_le_i32_e64 s[96:97], 0, v76
	v_cmp_le_i32_e64 s[100:101], 1, v76
	s_nop 0
	v_cndmask_b32_e64 v128, 0, v244, s[96:97]
	v_cndmask_b32_e64 v129, 0, v245, s[100:101]
	v_cmp_le_i32_e64 s[96:97], 2, v76
	v_cmp_le_i32_e64 s[100:101], 3, v76
	s_nop 0
	v_cndmask_b32_e64 v130, 0, v246, s[96:97]
	v_cndmask_b32_e64 v131, 0, v247, s[100:101]
	s_bfe_u32 s96, s62, 0x20006
	s_and_b32 s97, s96, 1
	s_mul_i32 s97, s97, 0x2700
	s_mov_b32 s101, 0x1c000
	s_mov_b32 s100, 0x6100
	s_bitcmp0_b32 s65, 0
	s_cselect_b32 s101, 0xe000, s101
	s_cselect_b32 s100, 0x4e00, s100
	s_cmp_gt_u32 s96, 1
	s_cselect_b32 s100, s100, 0
	s_add_i32 s97, s97, s101
	s_add_i32 s97, s97, s100
	v_xor_b32_e64 v74, v224, v234
	v_lshl_add_u32 v74, v74, 4, s97
	ds_write_b128 v74, v[128:131] offset:8448
	v_lshlrev_b32_e64 v75, 7, v234
	v_lshl_add_u32 v75, v233, 2, v75
	v_add_u32_e64 v75, s97, v75
	v_cmp_le_i32_e64 s[96:97], 0, v77
	v_cmp_le_i32_e64 s[100:101], 1, v77
	s_nop 0
	v_cndmask_b32_e64 v132, 0, v244, s[96:97]
	v_cndmask_b32_e64 v133, 0, v245, s[100:101]
	v_cmp_le_i32_e64 s[96:97], 2, v77
	v_cmp_le_i32_e64 s[100:101], 3, v77
	s_nop 0
	v_cndmask_b32_e64 v134, 0, v246, s[96:97]
	v_cndmask_b32_e64 v135, 0, v247, s[100:101]
	s_mov_b64 exec, 0x00ff00ff
	ds_write_b32 v75, v132 offset:9472
	ds_write_b32 v75, v133 offset:9504
	ds_write_b32 v75, v134 offset:9536
	ds_write_b32 v75, v135 offset:9568
	s_mov_b64 exec, -1
	s_setprio 0
	s_branch .LBB0_655
	s_nop 0
	s_nop 0
	s_nop 0
	s_nop 0
	s_nop 0
	s_nop 0
	s_nop 0
	s_nop 0
	s_nop 0
	s_nop 0
	s_nop 0
	s_nop 0
	s_nop 0
	s_nop 0
	s_nop 0
	s_nop 0
	s_nop 0
	s_nop 0
	s_nop 0
	s_nop 0
	s_nop 0
	s_nop 0
	s_nop 0
	s_nop 0
	s_nop 0
	s_nop 0
	s_nop 0
	s_nop 0
	s_nop 0
	s_nop 0
	s_nop 0
	s_nop 0
	s_nop 0
	s_nop 0
	s_nop 0
	s_nop 0
	s_nop 0
	s_nop 0
	s_nop 0
	s_nop 0
	s_nop 0
	s_nop 0
	s_nop 0
	s_nop 0
	s_nop 0
	s_nop 0
	s_nop 0
	s_nop 0
	s_nop 0
	s_nop 0
	s_nop 0
	s_nop 0
	s_nop 0
	s_nop 0
	s_nop 0
	s_nop 0
	s_nop 0
	s_nop 0
	s_nop 0
	s_nop 0
	s_nop 0
	s_nop 0
	s_nop 0
	s_nop 0
	s_nop 0
	s_nop 0
	s_nop 0
	s_nop 0
	s_nop 0
	s_nop 0
	s_nop 0
	s_nop 0
	s_nop 0
	s_nop 0
	s_nop 0
	s_nop 0
	s_nop 0
	s_nop 0
	s_nop 0
	s_nop 0
	s_nop 0
	s_nop 0
	s_nop 0
	s_nop 0
	s_nop 0
	s_nop 0
	s_nop 0
	s_nop 0
	s_nop 0
	s_nop 0
	s_nop 0
	s_nop 0
	s_nop 0
	s_nop 0
	s_nop 0
	s_nop 0
	s_nop 0
	s_nop 0
	s_nop 0
	s_nop 0
